# v25 + nt hint on the prep phase's per-row loads (pool window rows are re-read by neighbours, so this is a cache-policy experiment)
# baseline (speedup 1.0000x reference)
.LBB0_311:
	s_nop 0
	v_lshl_add_u64 v[44:45], s[70:71], 0, v[26:27]
	s_mov_b32 s2, 0x1d300000
	v_add_co_u32_e32 v46, vcc, s2, v44
	v_lshl_add_u64 v[48:49], s[70:71], 0, v[158:159]
	s_nop 0
	v_addc_co_u32_e32 v47, vcc, 0, v45, vcc
	global_load_dwordx4 v[76:79], v[46:47], off nt
	global_load_dwordx4 v[80:83], v[46:47], off offset:1664 nt
	global_load_dwordx2 v[164:165], v[48:49], off nt
	global_load_dwordx4 v[72:75], v[46:47], off offset:2688 nt
	v_add_co_u32_e32 v44, vcc, 0x1d301000, v44
	v_lshl_add_u64 v[50:51], s[70:71], 0, v[160:161]
	v_lshl_add_u64 v[46:47], s[70:71], 0, v[156:157]
	v_addc_co_u32_e32 v45, vcc, 0, v45, vcc
	global_load_ushort v84, v[50:51], off nt
	global_load_dwordx4 v[60:63], v[46:47], off nt
	s_nop 0
	global_load_dwordx4 v[48:51], v[44:45], off offset:128 nt
	s_nop 0
	global_load_dwordx4 v[44:47], v[44:45], off offset:1152 nt
	s_cmpk_lt_i32 s4, 0x2000
	s_cselect_b64 s[8:9], -1, 0
	s_cmpk_gt_i32 s4, 0x1fff
	s_cselect_b64 s[52:53], -1, 0
	s_and_b64 vcc, s[52:53], exec
	s_movk_i32 s2, 0xff
	s_cselect_b32 s2, s2, 0xfff
	s_and_b32 s2, s2, s4
	s_lshr_b32 s3, s2, 6
	s_and_b32 s5, s4, 63
	v_mov_b32_e32 v53, 0
	v_mov_b32_e32 v52, 1.0
	v_mov_b32_e32 v162, 1.0
	v_mov_b32_e32 v163, 0
	s_cbranch_vccnz .LBB0_313
	v_mov_b32_e32 v54, s5
	v_mov_b32_e32 v55, s3
	v_cndmask_b32_e64 v54, v54, v55, s[38:39]
	v_lshlrev_b32_e32 v55, 3, v166
	v_readlane_b32 s6, v251, 33
	v_lshl_or_b32 v54, v54, 7, v55
	v_readlane_b32 s7, v251, 34
	s_nop 4
	global_load_dwordx2 v[162:163], v54, s[6:7] nt
.LBB0_313:
	v_mov_b32_e32 v54, s5
	v_mov_b32_e32 v55, s3
	v_cndmask_b32_e64 v54, v54, v55, s[42:43]
	v_lshlrev_b32_e32 v96, 7, v54
	v_cndmask_b32_e64 v54, 0, 1, s[8:9]
	v_lshl_add_u64 v[68:69], v[136:137], 0, v[96:97]
	v_cmp_ne_u32_e64 s[50:51], 1, v54
	s_andn2_b64 vcc, exec, s[8:9]
	v_mov_b32_e32 v54, 1.0
	v_mov_b32_e32 v55, 0
	s_cbranch_vccnz .LBB0_315
	global_load_dwordx4 v[52:55], v[68:69], off nt
.LBB0_315:
	v_mov_b32_e32 v57, 0
	v_mov_b32_e32 v56, 1.0
	s_and_b64 vcc, exec, s[50:51]
	v_mov_b32_e32 v64, 1.0
	v_mov_b32_e32 v65, 0
	v_mov_b32_e32 v66, 1.0
	v_mov_b32_e32 v67, 0
	s_cbranch_vccnz .LBB0_319
	global_load_dwordx4 v[64:67], v[68:69], off offset:16 nt
	s_and_b64 vcc, exec, s[50:51]
	v_mov_b32_e32 v58, 1.0
	v_mov_b32_e32 v59, 0
	s_cbranch_vccz .LBB0_320

.LBB0_318:
	global_load_dwordx4 v[68:71], v[68:69], off offset:48 nt
	s_movk_i32 s3, 0x1000
	s_branch .LBB0_322

.LBB0_320:
	global_load_dwordx4 v[56:59], v[68:69], off offset:32 nt
	s_and_b64 vcc, exec, s[50:51]
	s_cbranch_vccz .LBB0_318

.LBB0_322:
	s_add_i32 s6, s4, 0xffffe000
	s_ashr_i32 s5, s4, 12
	s_lshr_b32 s8, s6, 8
	v_add_u32_e32 v85, s2, v168
	s_and_b64 s[6:7], s[52:53], exec
	s_waitcnt vmcnt(3)
	v_lshlrev_b32_e32 v96, 16, v84
	v_sub_u32_e32 v84, s2, v168
	v_min_i32_e32 v183, s3, v85
	s_cselect_b32 s5, s8, s5
	s_or_b32 s8, s2, 0x1000
	v_max_i32_e32 v184, 0, v84
	v_add_u32_e32 v130, -1, v183
	s_and_b64 s[6:7], s[52:53], exec
	v_min_i32_e32 v84, v184, v130
	s_movk_i32 s3, 0x1e00
	s_cselect_b32 s40, s8, s2
	v_mad_i64_i32 v[84:85], s[6:7], v84, s3, 0
	s_mulk_i32 s2, 0x1e00
	v_subrev_co_u32_e32 v84, vcc, s2, v84
	s_mov_b32 s8, 0x1d300000
	s_nop 0
	v_subbrev_co_u32_e32 v85, vcc, 0, v85, vcc
	v_lshl_add_u64 v[84:85], v[26:27], 0, v[84:85]
	v_lshl_add_u64 v[84:85], s[70:71], 0, v[84:85]
	v_add_u32_e32 v185, 1, v184
	v_add_co_u32_e32 v84, vcc, s8, v84
	v_min_i32_e32 v86, v185, v130
	s_nop 0
	v_addc_co_u32_e32 v85, vcc, 0, v85, vcc
	v_mad_i64_i32 v[86:87], s[6:7], v86, s3, 0
	v_subrev_co_u32_e32 v86, vcc, s2, v86
	v_add_u32_e32 v198, 2, v184
	s_nop 0
	v_subbrev_co_u32_e32 v87, vcc, 0, v87, vcc
	v_lshl_add_u64 v[86:87], v[26:27], 0, v[86:87]
	v_lshl_add_u64 v[86:87], s[70:71], 0, v[86:87]
	v_add_co_u32_e32 v86, vcc, s8, v86
	v_add_u32_e32 v199, 3, v184
	s_nop 0
	v_addc_co_u32_e32 v87, vcc, 0, v87, vcc
	global_load_dwordx4 v[186:189], v[84:85], off offset:1664 nt
	global_load_dwordx4 v[190:193], v[86:87], off offset:1664 nt
	v_min_i32_e32 v84, v198, v130
	v_mad_i64_i32 v[84:85], s[6:7], v84, s3, 0
	v_subrev_co_u32_e32 v84, vcc, s2, v84
	v_min_i32_e32 v86, v199, v130
	s_nop 0
	v_subbrev_co_u32_e32 v85, vcc, 0, v85, vcc
	v_lshl_add_u64 v[84:85], v[26:27], 0, v[84:85]
	v_lshl_add_u64 v[84:85], s[70:71], 0, v[84:85]
	v_add_co_u32_e32 v84, vcc, s8, v84
	v_mad_i64_i32 v[86:87], s[6:7], v86, s3, 0
	s_nop 0
	v_addc_co_u32_e32 v85, vcc, 0, v85, vcc
	v_subrev_co_u32_e32 v86, vcc, s2, v86
	v_add_u32_e32 v200, 4, v184
	s_nop 0
	v_subbrev_co_u32_e32 v87, vcc, 0, v87, vcc
	v_lshl_add_u64 v[86:87], v[26:27], 0, v[86:87]
	v_lshl_add_u64 v[86:87], s[70:71], 0, v[86:87]
	v_add_co_u32_e32 v86, vcc, s8, v86
	v_add_u32_e32 v201, 5, v184
	s_nop 0
	v_addc_co_u32_e32 v87, vcc, 0, v87, vcc
	global_load_dwordx4 v[214:217], v[84:85], off offset:1664 nt
	global_load_dwordx4 v[218:221], v[86:87], off offset:1664 nt
	v_min_i32_e32 v84, v200, v130
	v_mad_i64_i32 v[84:85], s[6:7], v84, s3, 0
	v_subrev_co_u32_e32 v84, vcc, s2, v84
	v_min_i32_e32 v86, v201, v130
	s_nop 0
	v_subbrev_co_u32_e32 v85, vcc, 0, v85, vcc
	v_lshl_add_u64 v[84:85], v[26:27], 0, v[84:85]
	v_lshl_add_u64 v[84:85], s[70:71], 0, v[84:85]
	v_add_co_u32_e32 v84, vcc, s8, v84
	v_mad_i64_i32 v[86:87], s[6:7], v86, s3, 0
	s_nop 0
	v_addc_co_u32_e32 v85, vcc, 0, v85, vcc
	v_subrev_co_u32_e32 v86, vcc, s2, v86
	v_add_u32_e32 v223, 6, v184
	s_nop 0
	v_subbrev_co_u32_e32 v87, vcc, 0, v87, vcc
	v_lshl_add_u64 v[86:87], v[26:27], 0, v[86:87]
	v_lshl_add_u64 v[86:87], s[70:71], 0, v[86:87]
	v_add_co_u32_e32 v86, vcc, s8, v86
	v_min_i32_e32 v92, v223, v130
	s_nop 0
	v_addc_co_u32_e32 v87, vcc, 0, v87, vcc
	v_mad_i64_i32 v[92:93], s[6:7], v92, s3, 0
	v_subrev_co_u32_e32 v92, vcc, s2, v92
	v_add_u32_e32 v229, 7, v184
	s_nop 0
	v_subbrev_co_u32_e32 v93, vcc, 0, v93, vcc
	v_lshl_add_u64 v[92:93], v[26:27], 0, v[92:93]
	v_lshl_add_u64 v[92:93], s[70:71], 0, v[92:93]
	v_add_co_u32_e32 v92, vcc, s8, v92
	v_min_i32_e32 v94, v229, v130
	s_nop 0
	v_addc_co_u32_e32 v93, vcc, 0, v93, vcc
	v_mad_i64_i32 v[94:95], s[6:7], v94, s3, 0
	v_subrev_co_u32_e32 v94, vcc, s2, v94
	v_add_u32_e32 v231, 8, v184
	s_nop 0
	v_subbrev_co_u32_e32 v95, vcc, 0, v95, vcc
	v_lshl_add_u64 v[94:95], v[26:27], 0, v[94:95]
	v_lshl_add_u64 v[94:95], s[70:71], 0, v[94:95]
	v_add_co_u32_e32 v94, vcc, s8, v94
	global_load_dwordx4 v[88:91], v[84:85], off offset:1664 nt
	s_nop 0
	global_load_dwordx4 v[84:87], v[86:87], off offset:1664 nt
	v_addc_co_u32_e32 v95, vcc, 0, v95, vcc
	global_load_dwordx4 v[102:105], v[92:93], off offset:1664 nt
	global_load_dwordx4 v[98:101], v[94:95], off offset:1664 nt
	v_min_i32_e32 v92, v231, v130
	v_mad_i64_i32 v[92:93], s[6:7], v92, s3, 0
	v_subrev_co_u32_e32 v92, vcc, s2, v92
	v_add_u32_e32 v233, 9, v184
	s_nop 0
	v_subbrev_co_u32_e32 v93, vcc, 0, v93, vcc
	v_lshl_add_u64 v[92:93], v[26:27], 0, v[92:93]
	v_lshl_add_u64 v[92:93], s[70:71], 0, v[92:93]
	v_add_co_u32_e32 v92, vcc, s8, v92
	v_min_i32_e32 v94, v233, v130
	s_nop 0
	v_addc_co_u32_e32 v93, vcc, 0, v93, vcc
	v_mad_i64_i32 v[94:95], s[6:7], v94, s3, 0
	v_subrev_co_u32_e32 v94, vcc, s2, v94
	v_add_u32_e32 v235, 10, v184
	s_nop 0
	v_subbrev_co_u32_e32 v95, vcc, 0, v95, vcc
	v_lshl_add_u64 v[94:95], v[26:27], 0, v[94:95]
	v_lshl_add_u64 v[94:95], s[70:71], 0, v[94:95]
	v_add_co_u32_e32 v94, vcc, s8, v94
	v_add_u32_e32 v237, 11, v184
	s_nop 0
	v_addc_co_u32_e32 v95, vcc, 0, v95, vcc
	global_load_dwordx4 v[110:113], v[92:93], off offset:1664 nt
	global_load_dwordx4 v[106:109], v[94:95], off offset:1664 nt
	v_min_i32_e32 v92, v235, v130
	v_mad_i64_i32 v[92:93], s[6:7], v92, s3, 0
	v_subrev_co_u32_e32 v92, vcc, s2, v92
	v_min_i32_e32 v94, v237, v130
	s_nop 0
	v_subbrev_co_u32_e32 v93, vcc, 0, v93, vcc
	v_lshl_add_u64 v[92:93], v[26:27], 0, v[92:93]
	v_lshl_add_u64 v[92:93], s[70:71], 0, v[92:93]
	v_add_co_u32_e32 v92, vcc, s8, v92
	v_mad_i64_i32 v[94:95], s[6:7], v94, s3, 0
	s_nop 0
	v_addc_co_u32_e32 v93, vcc, 0, v93, vcc
	v_subrev_co_u32_e32 v94, vcc, s2, v94
	v_add_u32_e32 v239, 12, v184
	s_nop 0
	v_subbrev_co_u32_e32 v95, vcc, 0, v95, vcc
	v_lshl_add_u64 v[94:95], v[26:27], 0, v[94:95]
	v_lshl_add_u64 v[94:95], s[70:71], 0, v[94:95]
	v_add_co_u32_e32 v94, vcc, s8, v94
	v_add_u32_e32 v241, 13, v184
	s_nop 0
	v_addc_co_u32_e32 v95, vcc, 0, v95, vcc
	global_load_dwordx4 v[122:125], v[92:93], off offset:1664 nt
	global_load_dwordx4 v[118:121], v[94:95], off offset:1664 nt
	v_min_i32_e32 v92, v239, v130
	v_mad_i64_i32 v[92:93], s[6:7], v92, s3, 0
	v_subrev_co_u32_e32 v92, vcc, s2, v92
	v_min_i32_e32 v94, v241, v130
	s_nop 0
	v_subbrev_co_u32_e32 v93, vcc, 0, v93, vcc
	v_lshl_add_u64 v[92:93], v[26:27], 0, v[92:93]
	v_lshl_add_u64 v[92:93], s[70:71], 0, v[92:93]
	v_add_co_u32_e32 v92, vcc, s8, v92
	v_mad_i64_i32 v[94:95], s[6:7], v94, s3, 0
	s_nop 0
	v_addc_co_u32_e32 v93, vcc, 0, v93, vcc
	v_subrev_co_u32_e32 v94, vcc, s2, v94
	v_add_u32_e32 v243, 14, v184
	s_nop 0
	v_subbrev_co_u32_e32 v95, vcc, 0, v95, vcc
	v_lshl_add_u64 v[94:95], v[26:27], 0, v[94:95]
	v_lshl_add_u64 v[94:95], s[70:71], 0, v[94:95]
	v_add_co_u32_e32 v94, vcc, s8, v94
	v_add_u32_e32 v245, 15, v184
	s_nop 0
	v_addc_co_u32_e32 v95, vcc, 0, v95, vcc
	global_load_dwordx4 v[126:129], v[92:93], off offset:1664 nt
	global_load_dwordx4 v[114:117], v[94:95], off offset:1664 nt
	v_min_i32_e32 v92, v243, v130
	v_mad_i64_i32 v[92:93], s[6:7], v92, s3, 0
	v_subrev_co_u32_e32 v92, vcc, s2, v92
	v_min_i32_e32 v94, v245, v130
	s_nop 0
	v_subbrev_co_u32_e32 v93, vcc, 0, v93, vcc
	v_lshl_add_u64 v[92:93], v[26:27], 0, v[92:93]
	v_lshl_add_u64 v[92:93], s[70:71], 0, v[92:93]
	v_add_co_u32_e32 v92, vcc, s8, v92
	v_mad_i64_i32 v[94:95], s[6:7], v94, s3, 0
	s_nop 0
	v_addc_co_u32_e32 v93, vcc, 0, v93, vcc
	v_subrev_co_u32_e32 v94, vcc, s2, v94
	s_waitcnt vmcnt(13)
	v_lshlrev_b32_e32 v181, 16, v187
	v_subbrev_co_u32_e32 v95, vcc, 0, v95, vcc
	v_lshl_add_u64 v[94:95], v[26:27], 0, v[94:95]
	v_lshl_add_u64 v[94:95], s[70:71], 0, v[94:95]
	v_add_co_u32_e32 v94, vcc, s8, v94
	v_lshlrev_b32_e32 v180, 16, v186
	s_nop 0
	v_addc_co_u32_e32 v95, vcc, 0, v95, vcc
	global_load_dwordx4 v[130:133], v[92:93], off offset:1664 nt
	s_nop 0
	global_load_dwordx4 v[92:95], v[94:95], off offset:1664 nt
	v_cmp_gt_i32_e32 vcc, v183, v184
	v_and_b32_e32 v187, 0xffff0000, v187
	v_and_b32_e32 v186, 0xffff0000, v186
	v_cndmask_b32_e64 v178, 0, 1.0, vcc
	v_lshlrev_b32_e32 v195, 16, v189
	v_lshlrev_b32_e32 v194, 16, v188
	v_and_b32_e32 v189, 0xffff0000, v189
	v_and_b32_e32 v188, 0xffff0000, v188
	v_cmp_lt_i32_e32 vcc, v185, v183
	v_pk_fma_f32 v[180:181], v[178:179], v[180:181], 0 op_sel_hi:[0,1,0]
	v_pk_fma_f32 v[186:187], v[178:179], v[186:187], 0 op_sel_hi:[0,1,0]
	v_pk_fma_f32 v[194:195], v[178:179], v[194:195], 0 op_sel_hi:[0,1,0]
	v_pk_fma_f32 v[178:179], v[178:179], v[188:189], 0 op_sel_hi:[0,1,0]
	v_cndmask_b32_e64 v188, 0, 1.0, vcc
	s_waitcnt vmcnt(14)
	v_lshlrev_b32_e32 v203, 16, v191
	v_lshlrev_b32_e32 v202, 16, v190
	v_and_b32_e32 v191, 0xffff0000, v191
	v_and_b32_e32 v190, 0xffff0000, v190
	v_cmp_lt_i32_e32 vcc, v198, v183
	s_waitcnt vmcnt(13)
	v_lshlrev_b32_e32 v207, 16, v215
	v_lshlrev_b32_e32 v206, 16, v214
	v_and_b32_e32 v209, 0xffff0000, v215
	v_and_b32_e32 v208, 0xffff0000, v214
	v_cndmask_b32_e64 v222, 0, 1.0, vcc
	v_cmp_lt_i32_e32 vcc, v199, v183
	v_pk_fma_f32 v[180:181], v[188:189], v[202:203], v[180:181] op_sel_hi:[0,1,1]
	v_pk_fma_f32 v[186:187], v[188:189], v[190:191], v[186:187] op_sel_hi:[0,1,1]
	s_waitcnt vmcnt(12)
	v_lshlrev_b32_e32 v224, 16, v218
	v_and_b32_e32 v218, 0xffff0000, v218
	v_lshlrev_b32_e32 v225, 16, v219
	v_and_b32_e32 v219, 0xffff0000, v219
	v_cndmask_b32_e64 v228, 0, 1.0, vcc
	v_cmp_lt_i32_e32 vcc, v200, v183
	v_pk_fma_f32 v[180:181], v[222:223], v[206:207], v[180:181] op_sel_hi:[0,1,1]
	v_pk_fma_f32 v[186:187], v[222:223], v[208:209], v[186:187] op_sel_hi:[0,1,1]
	v_cndmask_b32_e64 v230, 0, 1.0, vcc
	v_cmp_lt_i32_e32 vcc, v201, v183
	v_pk_fma_f32 v[180:181], v[228:229], v[224:225], v[180:181] op_sel_hi:[0,1,1]
	s_waitcnt vmcnt(11)
	v_lshlrev_b32_e32 v203, 16, v89
	v_lshlrev_b32_e32 v202, 16, v88
	v_pk_fma_f32 v[186:187], v[228:229], v[218:219], v[186:187] op_sel_hi:[0,1,1]
	v_and_b32_e32 v89, 0xffff0000, v89
	v_and_b32_e32 v88, 0xffff0000, v88
	v_cndmask_b32_e64 v232, 0, 1.0, vcc
	v_cmp_lt_i32_e32 vcc, v223, v183
	v_pk_fma_f32 v[180:181], v[230:231], v[202:203], v[180:181] op_sel_hi:[0,1,1]
	s_waitcnt vmcnt(10)
	v_lshlrev_b32_e32 v203, 16, v85
	v_lshlrev_b32_e32 v202, 16, v84
	v_pk_fma_f32 v[88:89], v[230:231], v[88:89], v[186:187] op_sel_hi:[0,1,1]
	v_and_b32_e32 v85, 0xffff0000, v85
	v_and_b32_e32 v84, 0xffff0000, v84
	v_cndmask_b32_e64 v234, 0, 1.0, vcc
	v_cmp_lt_i32_e32 vcc, v229, v183
	v_pk_fma_f32 v[84:85], v[232:233], v[84:85], v[88:89] op_sel_hi:[0,1,1]
	s_waitcnt vmcnt(9)
	v_and_b32_e32 v89, 0xffff0000, v103
	v_and_b32_e32 v88, 0xffff0000, v102
	v_cndmask_b32_e64 v236, 0, 1.0, vcc
	v_cmp_lt_i32_e32 vcc, v231, v183
	v_pk_fma_f32 v[84:85], v[234:235], v[88:89], v[84:85] op_sel_hi:[0,1,1]
	s_waitcnt vmcnt(8)
	v_and_b32_e32 v89, 0xffff0000, v99
	v_and_b32_e32 v88, 0xffff0000, v98
	v_cndmask_b32_e64 v238, 0, 1.0, vcc
	v_cmp_lt_i32_e32 vcc, v233, v183
	v_pk_fma_f32 v[84:85], v[236:237], v[88:89], v[84:85] op_sel_hi:[0,1,1]
	s_waitcnt vmcnt(7)
	v_and_b32_e32 v89, 0xffff0000, v111
	v_and_b32_e32 v88, 0xffff0000, v110
	v_cndmask_b32_e64 v240, 0, 1.0, vcc
	v_cmp_lt_i32_e32 vcc, v235, v183
	v_pk_fma_f32 v[84:85], v[238:239], v[88:89], v[84:85] op_sel_hi:[0,1,1]
	s_waitcnt vmcnt(6)
	v_and_b32_e32 v89, 0xffff0000, v107
	v_and_b32_e32 v88, 0xffff0000, v106
	v_cndmask_b32_e64 v242, 0, 1.0, vcc
	v_cmp_lt_i32_e32 vcc, v237, v183
	v_pk_fma_f32 v[84:85], v[240:241], v[88:89], v[84:85] op_sel_hi:[0,1,1]
	s_waitcnt vmcnt(5)
	v_and_b32_e32 v89, 0xffff0000, v123
	v_and_b32_e32 v88, 0xffff0000, v122
	v_lshlrev_b32_e32 v205, 16, v193
	v_lshlrev_b32_e32 v204, 16, v192
	v_cndmask_b32_e64 v244, 0, 1.0, vcc
	v_pk_fma_f32 v[84:85], v[242:243], v[88:89], v[84:85] op_sel_hi:[0,1,1]
	s_waitcnt vmcnt(4)
	v_and_b32_e32 v89, 0xffff0000, v119
	v_and_b32_e32 v88, 0xffff0000, v118
	v_lshlrev_b32_e32 v215, 16, v217
	v_lshlrev_b32_e32 v214, 16, v216
	v_pk_fma_f32 v[84:85], v[244:245], v[88:89], v[84:85] op_sel_hi:[0,1,1]
	v_pk_fma_f32 v[88:89], v[188:189], v[204:205], v[194:195] op_sel_hi:[0,1,1]
	v_lshlrev_b32_e32 v226, 16, v220
	v_lshlrev_b32_e32 v227, 16, v221
	v_pk_fma_f32 v[180:181], v[232:233], v[202:203], v[180:181] op_sel_hi:[0,1,1]
	v_lshlrev_b32_e32 v203, 16, v103
	v_lshlrev_b32_e32 v202, 16, v102
	v_pk_fma_f32 v[88:89], v[222:223], v[214:215], v[88:89] op_sel_hi:[0,1,1]
	v_pk_fma_f32 v[180:181], v[234:235], v[202:203], v[180:181] op_sel_hi:[0,1,1]
	v_lshlrev_b32_e32 v203, 16, v99
	v_lshlrev_b32_e32 v202, 16, v98
	v_pk_fma_f32 v[88:89], v[228:229], v[226:227], v[88:89] op_sel_hi:[0,1,1]
	v_lshlrev_b32_e32 v99, 16, v91
	v_lshlrev_b32_e32 v98, 16, v90
	v_pk_fma_f32 v[88:89], v[230:231], v[98:99], v[88:89] op_sel_hi:[0,1,1]
	v_lshlrev_b32_e32 v99, 16, v87
	v_lshlrev_b32_e32 v98, 16, v86
	v_pk_fma_f32 v[88:89], v[232:233], v[98:99], v[88:89] op_sel_hi:[0,1,1]
	v_lshlrev_b32_e32 v99, 16, v105
	v_lshlrev_b32_e32 v98, 16, v104
	v_pk_fma_f32 v[88:89], v[234:235], v[98:99], v[88:89] op_sel_hi:[0,1,1]
	v_lshlrev_b32_e32 v99, 16, v101
	v_lshlrev_b32_e32 v98, 16, v100
	v_pk_fma_f32 v[88:89], v[236:237], v[98:99], v[88:89] op_sel_hi:[0,1,1]
	v_lshlrev_b32_e32 v99, 16, v113
	v_lshlrev_b32_e32 v98, 16, v112
	v_pk_fma_f32 v[88:89], v[238:239], v[98:99], v[88:89] op_sel_hi:[0,1,1]
	v_lshlrev_b32_e32 v99, 16, v109
	v_lshlrev_b32_e32 v98, 16, v108
	v_pk_fma_f32 v[88:89], v[240:241], v[98:99], v[88:89] op_sel_hi:[0,1,1]
	v_lshlrev_b32_e32 v99, 16, v125
	v_lshlrev_b32_e32 v98, 16, v124
	v_and_b32_e32 v193, 0xffff0000, v193
	v_and_b32_e32 v192, 0xffff0000, v192
	v_pk_fma_f32 v[88:89], v[242:243], v[98:99], v[88:89] op_sel_hi:[0,1,1]
	v_lshlrev_b32_e32 v99, 16, v121
	v_lshlrev_b32_e32 v98, 16, v120
	v_and_b32_e32 v217, 0xffff0000, v217
	v_and_b32_e32 v216, 0xffff0000, v216
	v_pk_fma_f32 v[88:89], v[244:245], v[98:99], v[88:89] op_sel_hi:[0,1,1]
	v_pk_fma_f32 v[98:99], v[188:189], v[192:193], v[178:179] op_sel_hi:[0,1,1]
	v_and_b32_e32 v220, 0xffff0000, v220
	v_and_b32_e32 v221, 0xffff0000, v221
	v_pk_fma_f32 v[98:99], v[222:223], v[216:217], v[98:99] op_sel_hi:[0,1,1]
	v_pk_fma_f32 v[98:99], v[228:229], v[220:221], v[98:99] op_sel_hi:[0,1,1]
	v_and_b32_e32 v91, 0xffff0000, v91
	v_and_b32_e32 v90, 0xffff0000, v90
	v_pk_fma_f32 v[90:91], v[230:231], v[90:91], v[98:99] op_sel_hi:[0,1,1]
	v_and_b32_e32 v87, 0xffff0000, v87
	v_and_b32_e32 v86, 0xffff0000, v86
	v_pk_fma_f32 v[86:87], v[232:233], v[86:87], v[90:91] op_sel_hi:[0,1,1]
	v_and_b32_e32 v91, 0xffff0000, v105
	v_and_b32_e32 v90, 0xffff0000, v104
	v_pk_fma_f32 v[86:87], v[234:235], v[90:91], v[86:87] op_sel_hi:[0,1,1]
	v_and_b32_e32 v91, 0xffff0000, v101
	v_and_b32_e32 v90, 0xffff0000, v100
	v_pk_fma_f32 v[86:87], v[236:237], v[90:91], v[86:87] op_sel_hi:[0,1,1]
	v_and_b32_e32 v91, 0xffff0000, v113
	v_and_b32_e32 v90, 0xffff0000, v112
	v_pk_fma_f32 v[86:87], v[238:239], v[90:91], v[86:87] op_sel_hi:[0,1,1]
	v_and_b32_e32 v91, 0xffff0000, v109
	v_and_b32_e32 v90, 0xffff0000, v108
	v_pk_fma_f32 v[86:87], v[240:241], v[90:91], v[86:87] op_sel_hi:[0,1,1]
	v_and_b32_e32 v91, 0xffff0000, v125
	v_and_b32_e32 v90, 0xffff0000, v124
	v_pk_fma_f32 v[86:87], v[242:243], v[90:91], v[86:87] op_sel_hi:[0,1,1]
	v_and_b32_e32 v91, 0xffff0000, v121
	v_and_b32_e32 v90, 0xffff0000, v120
	v_pk_fma_f32 v[86:87], v[244:245], v[90:91], v[86:87] op_sel_hi:[0,1,1]
	v_sub_u32_e32 v91, v183, v184
	v_cvt_f32_i32_e32 v91, v91
	v_pk_fma_f32 v[180:181], v[236:237], v[202:203], v[180:181] op_sel_hi:[0,1,1]
	v_lshlrev_b32_e32 v203, 16, v111
	v_lshlrev_b32_e32 v202, 16, v110
	v_cmp_lt_i32_e32 vcc, v239, v183
	v_pk_fma_f32 v[180:181], v[238:239], v[202:203], v[180:181] op_sel_hi:[0,1,1]
	v_lshlrev_b32_e32 v203, 16, v107
	v_lshlrev_b32_e32 v202, 16, v106
	v_cndmask_b32_e64 v90, 0, 1.0, vcc
	s_waitcnt vmcnt(3)
	v_and_b32_e32 v101, 0xffff0000, v127
	v_and_b32_e32 v100, 0xffff0000, v126
	v_cmp_lt_i32_e32 vcc, v241, v183
	v_pk_fma_f32 v[180:181], v[240:241], v[202:203], v[180:181] op_sel_hi:[0,1,1]
	v_lshlrev_b32_e32 v203, 16, v123
	v_lshlrev_b32_e32 v202, 16, v122
	v_lshlrev_b32_e32 v102, 16, v128
	v_and_b32_e32 v104, 0xffff0000, v128
	s_waitcnt vmcnt(2)
	v_lshlrev_b32_e32 v106, 16, v114
	v_and_b32_e32 v109, 0xffff0000, v115
	v_and_b32_e32 v108, 0xffff0000, v114
	v_cndmask_b32_e64 v114, 0, 1.0, vcc
	v_cmp_lt_i32_e32 vcc, v243, v183
	v_rcp_iflag_f32_e32 v128, v91
	v_pk_fma_f32 v[84:85], v[90:91], v[100:101], v[84:85] op_sel_hi:[0,1,1]
	v_pk_fma_f32 v[180:181], v[242:243], v[202:203], v[180:181] op_sel_hi:[0,1,1]
	v_lshlrev_b32_e32 v203, 16, v119
	v_lshlrev_b32_e32 v202, 16, v118
	s_waitcnt vmcnt(1)
	v_and_b32_e32 v118, 0xffff0000, v130
	v_and_b32_e32 v119, 0xffff0000, v131
	v_cndmask_b32_e64 v124, 0, 1.0, vcc
	v_cmp_lt_i32_e32 vcc, v245, v183
	v_pk_fma_f32 v[84:85], v[114:115], v[108:109], v[84:85] op_sel_hi:[0,1,1]
	v_lshlrev_b32_e32 v98, 16, v126
	v_cndmask_b32_e64 v126, 0, 1.0, vcc
	v_pk_fma_f32 v[84:85], v[124:125], v[118:119], v[84:85] op_sel_hi:[0,1,1]
	s_waitcnt vmcnt(0)
	v_lshlrev_b32_e32 v101, 16, v93
	v_lshlrev_b32_e32 v100, 16, v92
	v_and_b32_e32 v93, 0xffff0000, v93
	v_and_b32_e32 v92, 0xffff0000, v92
	v_pk_fma_f32 v[180:181], v[244:245], v[202:203], v[180:181] op_sel_hi:[0,1,1]
	v_lshlrev_b32_e32 v99, 16, v127
	v_lshlrev_b32_e32 v103, 16, v129
	v_and_b32_e32 v105, 0xffff0000, v129
	v_pk_fma_f32 v[84:85], v[126:127], v[92:93], v[84:85] op_sel_hi:[0,1,1]
	v_lshlrev_b32_e32 v93, 16, v81
	v_lshlrev_b32_e32 v92, 16, v80
	v_and_b32_e32 v81, 0xffff0000, v81
	v_and_b32_e32 v80, 0xffff0000, v80
	v_lshlrev_b32_e32 v107, 16, v115
	v_lshlrev_b32_e32 v111, 16, v117
	v_lshlrev_b32_e32 v110, 16, v116
	v_and_b32_e32 v113, 0xffff0000, v117
	v_and_b32_e32 v112, 0xffff0000, v116
	v_pk_fma_f32 v[98:99], v[90:91], v[98:99], v[180:181] op_sel_hi:[0,1,1]
	v_pk_fma_f32 v[80:81], v[128:129], v[84:85], v[80:81] op_sel_hi:[0,1,1] neg_lo:[0,0,1] neg_hi:[0,0,1]
	v_pk_fma_f32 v[84:85], v[90:91], v[102:103], v[88:89] op_sel_hi:[0,1,1]
	v_pk_fma_f32 v[86:87], v[90:91], v[104:105], v[86:87] op_sel_hi:[0,1,1]
	v_lshlrev_b32_e32 v116, 16, v130
	v_lshlrev_b32_e32 v117, 16, v131
	v_lshlrev_b32_e32 v120, 16, v132
	v_and_b32_e32 v122, 0xffff0000, v132
	v_lshlrev_b32_e32 v121, 16, v133
	v_and_b32_e32 v123, 0xffff0000, v133
	v_pk_fma_f32 v[98:99], v[114:115], v[106:107], v[98:99] op_sel_hi:[0,1,1]
	v_pk_fma_f32 v[84:85], v[114:115], v[110:111], v[84:85] op_sel_hi:[0,1,1]
	v_pk_fma_f32 v[86:87], v[114:115], v[112:113], v[86:87] op_sel_hi:[0,1,1]
	v_pk_fma_f32 v[98:99], v[124:125], v[116:117], v[98:99] op_sel_hi:[0,1,1]
	v_pk_fma_f32 v[84:85], v[124:125], v[120:121], v[84:85] op_sel_hi:[0,1,1]
	v_pk_fma_f32 v[86:87], v[124:125], v[122:123], v[86:87] op_sel_hi:[0,1,1]
	v_lshlrev_b32_e32 v89, 16, v95
	v_lshlrev_b32_e32 v88, 16, v94
	v_and_b32_e32 v91, 0xffff0000, v95
	v_and_b32_e32 v90, 0xffff0000, v94
	v_pk_fma_f32 v[98:99], v[126:127], v[100:101], v[98:99] op_sel_hi:[0,1,1]
	v_pk_fma_f32 v[84:85], v[126:127], v[88:89], v[84:85] op_sel_hi:[0,1,1]
	v_pk_fma_f32 v[86:87], v[126:127], v[90:91], v[86:87] op_sel_hi:[0,1,1]
	v_lshlrev_b32_e32 v89, 16, v83
	v_lshlrev_b32_e32 v88, 16, v82
	v_and_b32_e32 v83, 0xffff0000, v83
	v_and_b32_e32 v82, 0xffff0000, v82
	v_pk_fma_f32 v[92:93], v[128:129], v[98:99], v[92:93] op_sel_hi:[0,1,1] neg_lo:[0,0,1] neg_hi:[0,0,1]
	v_pk_fma_f32 v[84:85], v[128:129], v[84:85], v[88:89] op_sel_hi:[0,1,1] neg_lo:[0,0,1] neg_hi:[0,0,1]
	v_pk_fma_f32 v[82:83], v[128:129], v[86:87], v[82:83] op_sel_hi:[0,1,1] neg_lo:[0,0,1] neg_hi:[0,0,1]
	v_bfe_u32 v89, v80, 16, 1
	v_bfe_u32 v86, v83, 16, 1
	v_bfe_u32 v87, v82, 16, 1
	v_bfe_u32 v88, v81, 16, 1
	v_add3_u32 v94, v80, v89, s78
	v_bfe_u32 v80, v92, 16, 1
	v_add3_u32 v95, v81, v88, s78
	v_add3_u32 v98, v82, v87, s78
	v_add3_u32 v99, v83, v86, s78
	v_bfe_u32 v81, v93, 16, 1
	v_bfe_u32 v82, v84, 16, 1
	v_bfe_u32 v83, v85, 16, 1
	v_add3_u32 v80, v92, v80, s78
	v_add3_u32 v100, v85, v83, s78
	v_add3_u32 v101, v84, v82, s78
	v_add3_u32 v93, v93, v81, s78
	v_lshrrev_b32_e32 v92, 16, v80
	v_lshlrev_b32_e32 v81, 16, v77
	v_lshlrev_b32_e32 v80, 16, v76
	v_and_b32_e32 v83, 0xffff0000, v77
	v_and_b32_e32 v82, 0xffff0000, v76
	v_pk_mul_f32 v[76:77], v[80:81], v[80:81]
	v_pk_mul_f32 v[84:85], v[82:83], v[82:83]
	v_lshlrev_b32_e32 v87, 16, v79
	v_add_f32_e32 v76, v76, v84
	v_lshlrev_b32_e32 v86, 16, v78
	v_add_f32_e32 v76, v77, v76
	v_and_b32_e32 v89, 0xffff0000, v79
	v_and_b32_e32 v88, 0xffff0000, v78
	v_pk_mul_f32 v[78:79], v[86:87], v[86:87]
	v_add_f32_e32 v76, v85, v76
	v_pk_mul_f32 v[90:91], v[88:89], v[88:89]
	v_add_f32_e32 v76, v78, v76
	v_add_f32_e32 v76, v90, v76
	v_add_f32_e32 v76, v79, v76
	v_add_f32_e32 v76, v91, v76
	v_lshrrev_b32_e32 v77, 16, v93
	v_lshrrev_b32_e32 v78, 16, v101
	v_add_f32_dpp v76, v76, v76 quad_perm:[1,0,3,2] row_mask:0xf bank_mask:0xf bound_ctrl:1
	v_lshrrev_b32_e32 v79, 16, v100
	v_and_or_b32 v79, v99, s79, v79
	v_add_f32_dpp v76, v76, v76 quad_perm:[2,3,0,1] row_mask:0xf bank_mask:0xf bound_ctrl:1
	v_and_or_b32 v78, v98, s79, v78
	v_and_or_b32 v77, v95, s79, v77
	v_add_f32_dpp v76, v76, v76 row_half_mirror row_mask:0xf bank_mask:0xf bound_ctrl:1
	v_lshl_add_u64 v[90:91], s[70:71], 0, v[154:155]
	s_nop 0
	v_add_f32_dpp v76, v76, v76 row_mirror row_mask:0xf bank_mask:0xf bound_ctrl:1
	v_cvt_i32_f32_e32 v76, v76
	s_nop 0
	v_readlane_b32 s2, v76, 0
	v_readlane_b32 s3, v76, 16
	v_readlane_b32 s6, v76, 32
	s_add_i32 s2, s3, s2
	v_readlane_b32 s7, v76, 48
	s_add_i32 s2, s2, s6
	s_add_i32 s2, s2, s7
	v_cvt_f32_i32_e32 v76, s2
	v_fmamk_f32 v76, v76, 0x3b000000, v196
	v_rsq_f32_e32 v84, v76
	v_and_or_b32 v76, v94, s79, v92
	global_store_dwordx4 v[90:91], v[76:79], off
	s_nop 1
	v_pk_mul_f32 v[78:79], v[84:85], v[82:83] op_sel_hi:[0,1]
	v_pk_mul_f32 v[82:83], v[84:85], v[88:89] op_sel_hi:[0,1]
	v_pk_mul_f32 v[76:77], v[84:85], v[80:81] op_sel_hi:[0,1]
	v_pk_mul_f32 v[78:79], v[10:11], v[78:79]
	v_pk_mul_f32 v[80:81], v[84:85], v[86:87] op_sel_hi:[0,1]
	v_pk_mul_f32 v[82:83], v[22:23], v[82:83]
	v_pk_mul_f32 v[76:77], v[20:21], v[76:77]
	v_pk_mul_f32 v[80:81], v[16:17], v[80:81]
	v_bfe_u32 v84, v83, 16, 1
	v_bfe_u32 v85, v82, 16, 1
	v_bfe_u32 v87, v78, 16, 1
	v_bfe_u32 v86, v79, 16, 1
	v_add3_u32 v87, v78, v87, s78
	v_add3_u32 v85, v82, v85, s78
	v_add3_u32 v84, v83, v84, s78
	v_bfe_u32 v78, v76, 16, 1
	v_bfe_u32 v82, v80, 16, 1
	v_bfe_u32 v83, v81, 16, 1
	v_add3_u32 v86, v79, v86, s78
	v_bfe_u32 v79, v77, 16, 1
	v_add3_u32 v88, v81, v83, s78
	v_add3_u32 v89, v80, v82, s78
	v_add3_u32 v76, v76, v78, s78
	v_lshlrev_b32_e32 v81, 16, v165
	v_lshlrev_b32_e32 v80, 16, v164
	v_and_b32_e32 v83, 0xffff0000, v165
	v_and_b32_e32 v82, 0xffff0000, v164
	v_add3_u32 v90, v77, v79, s78
	v_lshrrev_b32_e32 v91, 16, v76
	v_pk_mul_f32 v[76:77], v[80:81], v[80:81]
	v_pk_mul_f32 v[78:79], v[82:83], v[82:83]
	s_nop 0
	v_add_f32_e32 v76, v76, v78
	v_add_f32_e32 v76, v77, v76
	v_add_f32_e32 v76, v79, v76
	v_lshrrev_b32_e32 v77, 16, v90
	v_lshrrev_b32_e32 v78, 16, v89
	v_add_f32_dpp v76, v76, v76 quad_perm:[1,0,3,2] row_mask:0xf bank_mask:0xf bound_ctrl:1
	v_lshrrev_b32_e32 v79, 16, v88
	v_and_or_b32 v79, v84, s79, v79
	v_add_f32_dpp v76, v76, v76 quad_perm:[2,3,0,1] row_mask:0xf bank_mask:0xf bound_ctrl:1
	v_and_or_b32 v78, v85, s79, v78
	v_and_or_b32 v77, v86, s79, v77
	v_add_f32_dpp v76, v76, v76 row_half_mirror row_mask:0xf bank_mask:0xf bound_ctrl:1
	s_nop 1
	v_add_f32_dpp v76, v76, v76 row_mirror row_mask:0xf bank_mask:0xf bound_ctrl:1
	v_cvt_i32_f32_e32 v76, v76
	s_nop 0
	v_readlane_b32 s2, v76, 0
	v_readlane_b32 s3, v76, 16
	v_readlane_b32 s6, v76, 32
	s_add_i32 s2, s3, s2
	v_readlane_b32 s7, v76, 48
	s_add_i32 s2, s2, s6
	s_add_i32 s2, s2, s7
	v_cvt_f32_i32_e32 v76, s2
	v_fmamk_f32 v76, v76, 0x3b800000, v196
	v_rsq_f32_e32 v84, v76
	v_and_or_b32 v76, v87, s79, v91
	v_lshl_add_u64 v[86:87], s[70:71], 0, v[152:153]
	global_store_dwordx4 v[86:87], v[76:79], off
	s_nop 1
	v_mul_f32_e32 v78, v96, v96
	v_mov_b32_e32 v79, v97
	v_pk_mul_f32 v[76:77], v[84:85], v[80:81] op_sel_hi:[0,1]
	v_pk_mul_f32 v[76:77], v[24:25], v[76:77]
	v_mov_b32_dpp v79, v78 quad_perm:[1,0,3,2] row_mask:0xf bank_mask:0xf
	v_fmac_f32_e32 v79, v96, v96
	v_and_b32_sdwa v81, v77, v197 dst_sel:DWORD dst_unused:UNUSED_PAD src0_sel:WORD_1 src1_sel:DWORD
	s_nop 0
	v_add_f32_dpp v78, v79, v79 quad_perm:[2,3,0,1] row_mask:0xf bank_mask:0xf bound_ctrl:1
	s_nop 1
	v_add_f32_dpp v78, v78, v78 row_half_mirror row_mask:0xf bank_mask:0xf bound_ctrl:1
	s_nop 1
	v_add_f32_dpp v78, v78, v78 row_mirror row_mask:0xf bank_mask:0xf bound_ctrl:1
	v_cvt_i32_f32_e32 v80, v78
	v_pk_mul_f32 v[78:79], v[84:85], v[82:83] op_sel_hi:[0,1]
	v_and_b32_sdwa v82, v76, v197 dst_sel:DWORD dst_unused:UNUSED_PAD src0_sel:WORD_1 src1_sel:DWORD
	v_add3_u32 v84, v76, v82, s78
	v_readlane_b32 s2, v80, 0
	v_readlane_b32 s3, v80, 16
	v_readlane_b32 s6, v80, 32
	s_add_i32 s2, s3, s2
	v_readlane_b32 s7, v80, 48
	s_add_i32 s2, s2, s6
	s_add_i32 s2, s2, s7
	v_cvt_f32_i32_e32 v80, s2
	v_add3_u32 v85, v77, v81, s78
	v_pk_mul_f32 v[78:79], v[18:19], v[78:79]
	v_fmamk_f32 v76, v80, 0x3c800000, v196
	v_rsq_f32_e32 v76, v76
	v_and_b32_sdwa v77, v79, v197 dst_sel:DWORD dst_unused:UNUSED_PAD src0_sel:WORD_1 src1_sel:DWORD
	v_add3_u32 v77, v79, v77, s78
	v_and_b32_e32 v86, 0xffff0000, v77
	v_mul_f32_e32 v76, v76, v96
	v_mul_f32_e32 v76, v135, v76
	ds_bpermute_b32 v81, v169, v76
	v_and_b32_sdwa v80, v78, v197 dst_sel:DWORD dst_unused:UNUSED_PAD src0_sel:WORD_1 src1_sel:DWORD
	v_add3_u32 v78, v78, v80, s78
	v_and_b32_e32 v87, 0xffff0000, v78
	v_or_b32_sdwa v85, v86, v85 dst_sel:DWORD dst_unused:UNUSED_PAD src0_sel:DWORD src1_sel:WORD_1
	s_waitcnt lgkmcnt(0)
	v_mul_f32_e32 v77, v163, v81
	v_cndmask_b32_e64 v77, v77, -v77, s[44:45]
	v_fmac_f32_e32 v77, v162, v76
	v_cndmask_b32_e64 v76, v77, v76, s[52:53]
	ds_bpermute_b32 v83, v171, v76
	ds_bpermute_b32 v82, v173, v76
	ds_bpermute_b32 v81, v174, v76
	ds_bpermute_b32 v80, v175, v76
	ds_bpermute_b32 v79, v176, v76
	ds_bpermute_b32 v78, v177, v76
	ds_bpermute_b32 v77, v182, v76
	ds_bpermute_b32 v76, v172, v76
	v_or_b32_sdwa v84, v87, v84 dst_sel:DWORD dst_unused:UNUSED_PAD src0_sel:DWORD src1_sel:WORD_1
	v_lshl_add_u64 v[86:87], s[70:71], 0, v[150:151]
	global_store_dwordx2 v[86:87], v[84:85], off
	s_and_saveexec_b64 s[8:9], s[46:47]
	s_cbranch_execz .LBB0_324
	s_waitcnt lgkmcnt(7)
	v_bfe_u32 v84, v83, 16, 1
	v_add3_u32 v83, v83, v84, s78
	s_waitcnt lgkmcnt(6)
	v_bfe_u32 v84, v82, 16, 1
	v_lshrrev_b32_e32 v83, 16, v83
	v_add3_u32 v82, v82, v84, s78
	v_and_or_b32 v82, v82, s79, v83
	s_waitcnt lgkmcnt(5)
	v_bfe_u32 v83, v81, 16, 1
	v_add3_u32 v81, v81, v83, s78
	s_waitcnt lgkmcnt(4)
	v_bfe_u32 v83, v80, 16, 1
	v_lshrrev_b32_e32 v81, 16, v81
	v_add3_u32 v80, v80, v83, s78
	v_and_or_b32 v83, v80, s79, v81
	s_waitcnt lgkmcnt(3)
	v_bfe_u32 v80, v79, 16, 1
	v_add3_u32 v79, v79, v80, s78
	s_waitcnt lgkmcnt(2)
	v_bfe_u32 v80, v78, 16, 1
	v_lshrrev_b32_e32 v79, 16, v79
	v_add3_u32 v78, v78, v80, s78
	v_and_or_b32 v84, v78, s79, v79
	s_waitcnt lgkmcnt(1)
	v_bfe_u32 v78, v77, 16, 1
	v_add3_u32 v77, v77, v78, s78
	s_waitcnt lgkmcnt(0)
	v_bfe_u32 v78, v76, 16, 1
	v_lshrrev_b32_e32 v77, 16, v77
	v_add3_u32 v76, v76, v78, s78
	v_and_or_b32 v85, v76, s79, v77
	s_lshl_b32 s7, s40, 1
	v_and_or_b32 v76, s40, 19, v170
	s_lshr_b32 s2, s40, 5
	s_lshr_b32 s10, s40, 1
	v_and_or_b32 v76, s7, 8, v76
	s_mulk_i32 s2, 0x3000
	s_mov_b32 s3, s41
	v_and_or_b32 v76, s10, 4, v76
	v_lshlrev_b32_e32 v96, 4, v76
	v_lshl_add_u64 v[76:77], v[146:147], 0, s[2:3]
	s_lshl_b32 s6, s5, 2
	v_lshl_add_u64 v[76:77], v[76:77], 0, v[96:97]
	v_mov_b32_e32 v80, 0x198000
	v_mad_i64_i32 v[78:79], s[2:3], s6, v80, v[76:77]
	s_or_b32 s2, s6, 1
	global_store_dwordx4 v[78:79], v[82:85], off
	v_mad_i64_i32 v[78:79], s[2:3], s2, v80, v[76:77]
	s_or_b32 s2, s6, 2
	global_store_dwordx4 v[78:79], v[82:85], off
	v_mad_i64_i32 v[78:79], s[2:3], s2, v80, v[76:77]
	s_or_b32 s2, s6, 3
	s_nop 0
	v_mad_i64_i32 v[76:77], s[2:3], s2, v80, v[76:77]
	global_store_dwordx4 v[78:79], v[82:85], off
	global_store_dwordx4 v[76:77], v[82:85], off
